# stack+ret_out-head-norm-reductions-via-DPP-adds-instead-of-ds_bpermute
# baseline (speedup 1.0000x reference)
; #define LAS __attribute__((address_space(3)))
; __device__ __forceinline__ void unpack8(u32x4 u, float* o) { o[0] = bflo(u.x); o[1] = bfhi(u.x); o[2] = bflo(u.y); o[3] = bfhi(u.y); o[4] = bflo(u.z); o[5] = bfhi(u.z); o[6] = bflo(u.w); o[7] = bfhi(u.w); }
; __device__ __forceinline__ u32x4 pack8u(const float* f) { u32x4 u; u.x = pk2(f[0], f[1]); u.y = pk2(f[2], f[3]); u.z = pk2(f[4], f[5]); u.w = pk2(f[6], f[7]); return u; }
; __device__ __forceinline__ void rot8(const bf16* src, const float* rot, int pos, int part, float scale, float* o1, float* o2) {
;     float x1[8], x2[8]; unpack8(*(const u32x4*)(src + 8 * part), x1); unpack8(*(const u32x4*)(src + 32 + 8 * part), x2);
;     const float* cs = rot + (size_t)pos * 32 + 8 * part; const float* sn = rot + (size_t)2048 * 32 + (size_t)pos * 32 + 8 * part;
;     const f32x4 c0 = *(const f32x4*)cs, c1 = *(const f32x4*)(cs + 4), s0 = *(const f32x4*)sn, s1 = *(const f32x4*)(sn + 4);
;     const float cv[8] = {c0.x, c0.y, c0.z, c0.w, c1.x, c1.y, c1.z, c1.w}, sv[8] = {s0.x, s0.y, s0.z, s0.w, s1.x, s1.y, s1.z, s1.w};
; #pragma unroll
;     for (int i = 0; i < 8; ++i) { o1[i] = (x1[i] * cv[i] - x2[i] * sv[i]) * scale; o2[i] = (x1[i] * sv[i] + x2[i] * cv[i]) * scale; }
; }
; __device__ __forceinline__ void ret_out_phase(int l, LAS unsigned char* lds, int wave, int lane_) {
;     ...
;         const int j = it % NRC, bh = it / NRC, b = bh >> 3, h = bh & 7;
;         const float l2g = ret_log2g(h);
;         const __amdgpu_buffer_rsrc_t strs = __builtin_amdgcn_make_buffer_rsrc((void*)(ws + OFF_ST), 0, 0x7fffffff, 0x00027000);
;         const unsigned sfo = (unsigned)(((bh * NRC + j) * 2 + 0) * 8192 * 2);
;         u32x4 sfv[4][2], sbv[4][2];
;     ...
;         RET_LD_STATES(0);
;         {
;             const int m = tid >> 2, part = tid & 3; const int pos = j * RC + m;
;             const bf16* src = rawB + ((size_t)b * SEQ + pos) * 2048 + h * 64;
;             float o1[8], o2[8];
;             rot8(src, rot, pos, part, 0.125f, o1, o2);
;             *(LAS u32x4*)(Qs + m * QP + 8 * part) = pack8u(o1); *(LAS u32x4*)(Qs + m * QP + 32 + 8 * part) = pack8u(o2);
;             rot8(src + 512, rot, pos, part, 1.0f, o1, o2);
;             *(LAS u32x4*)(Ks + m * QP + 8 * part) = pack8u(o1); *(LAS u32x4*)(Ks + m * QP + 32 + 8 * part) = pack8u(o2);
;             stage_vt(rawB, b, h, j, Vt, tid);
.LBB0_632:
	s_ashr_i32 s34, s46, 31
	s_lshr_b32 s34, s34, 28
	s_add_i32 s36, s46, s34
	s_ashr_i32 s37, s36, 4
	s_and_b32 s42, s37, 7
	v_cvt_f32_ubyte0_e32 v4, s42
	v_sub_f32_e32 v4, 0xc0a00000, v4
	v_cmp_gt_f32_e32 vcc, s50, v4
	s_and_b64 s[34:35], vcc, exec
	s_cselect_b32 s34, 0xffffffc0, 0
	v_cndmask_b32_e32 v5, 0, v206, vcc
	v_add_f32_e32 v4, v4, v5
	v_exp_f32_e32 v4, v4
	s_lshl_b32 s35, s37, 11
	v_ldexp_f32 v76, v4, s34
	s_ashr_i32 s34, s36, 7
	s_sub_i32 s36, s29, s35
	v_add_u32_e32 v78, s36, v94
	s_ashr_i32 s35, s34, 31
	s_lshl_b64 s[34:35], s[34:35], 11
	v_ashrrev_i32_e32 v79, 31, v78
	v_lshl_add_u64 v[68:69], s[34:35], 0, v[78:79]
	v_fmamk_f32 v77, v76, 0x3e800000, v201
	v_lshlrev_b64 v[68:69], 12, v[68:69]
	v_pk_mul_f32 v[4:5], v[76:77], v[76:77] op_sel_hi:[0,1]
	v_lshl_add_u64 v[68:69], s[44:45], 0, v[68:69]
	s_lshl_b32 s96, s42, 7
	v_add_f32_e32 v5, 0.5, v5
	v_lshl_add_u64 v[68:69], v[68:69], 0, s[96:97]
	v_fmac_f32_e32 v76, v4, v5
	v_lshl_add_u64 v[90:91], v[68:69], 0, v[2:3]
	v_lshlrev_b64 v[78:79], 7, v[78:79]
	v_lshl_add_u64 v[82:83], v[96:97], 0, v[78:79]
	v_lshl_add_u64 v[110:111], v[98:99], 0, v[78:79]
	s_ashr_i32 s37, s36, 31
	s_add_u32 s34, s34, s36
	s_addc_u32 s35, s35, s37
	s_nop 0
	global_load_dwordx4 v[68:71], v[90:91], off
	global_load_dwordx4 v[72:75], v[90:91], off offset:64
	global_load_dwordx4 v[78:81], v[82:83], off offset:16
	s_nop 0
	global_load_dwordx4 v[82:85], v[82:83], off
	s_nop 0
	global_load_dwordx4 v[86:89], v[110:111], off offset:16
	s_nop 0
	global_load_dwordx4 v[110:113], v[110:111], off
	s_lshl_b32 s96, s42, 8
	v_mov_b32_e32 v109, v3
	s_add_u32 s36, s6, s96
	s_addc_u32 s37, s7, 0
	global_load_dwordx4 v[224:227], v[90:91], off offset:1024
	global_load_dwordx4 v[228:231], v[90:91], off offset:1088
	v_lshl_add_u64 v[248:249], s[34:35], 0, v[94:95]
	v_lshlrev_b64 v[248:249], 12, v[248:249]
	v_lshl_add_u64 v[248:249], s[44:45], 0, v[248:249]
	v_lshl_add_u64 v[248:249], v[248:249], 0, s[96:97]
	v_lshl_add_u64 v[248:249], v[248:249], 0, v[108:109]
	global_load_dwordx4 v[232:235], v[248:249], off offset:2048
	global_load_dwordx4 v[236:239], v[248:249], off offset:2064
	global_load_dwordx4 v[240:243], v[248:249], off offset:2080
	global_load_dwordx4 v[244:247], v[248:249], off offset:2096
	v_add_u32_e32 v12, 0xffff8800, v161
	s_waitcnt vmcnt(17)
	v_add_u32_e32 v20, 0xffffcfc0, v161
	buffer_load_dwordx4 v[16:19], v12, s[60:63], 0 offen sc0 sc1
	s_waitcnt vmcnt(16)
	v_add_u32_e32 v28, 0xffff9000, v161
	buffer_load_dwordx4 v[20:23], v20, s[60:63], 0 offen sc0 sc1
	v_add_u32_e32 v12, 0xffffc800, v161
	v_add_u32_e32 v44, 0xffff9800, v161
	v_add_u32_e32 v52, 0xffffdfc0, v161
	buffer_load_dwordx4 v[24:27], v12, s[60:63], 0 offen sc0 sc1
	buffer_load_dwordx4 v[32:35], v28, s[60:63], 0 offen sc0 sc1
	v_add_u32_e32 v12, 0xffff8fc0, v161
	v_add_u32_e32 v28, 0xffffd000, v161
	buffer_load_dwordx4 v[48:51], v44, s[60:63], 0 offen sc0 sc1
	v_add_u32_e32 v60, 0xffffa000, v161
	buffer_load_dwordx4 v[52:55], v52, s[60:63], 0 offen sc0 sc1
	v_add_u32_e32 v44, 0xffffd800, v161
	v_add_u32_e32 v4, 0xffff87c0, v161
	v_add_u32_e32 v8, 0xffffc7c0, v161
	buffer_load_dwordx4 v[12:15], v12, s[60:63], 0 offen sc0 sc1
	s_waitcnt vmcnt(20)
	v_add_u32_e32 v36, 0xffffd7c0, v161
	buffer_load_dwordx4 v[40:43], v28, s[60:63], 0 offen sc0 sc1
	v_add_u32_e32 v28, 0xffff97c0, v161
	buffer_load_dwordx4 v[56:59], v44, s[60:63], 0 offen sc0 sc1
	v_add_u32_e32 v64, 0xffffe000, v161
	buffer_load_dwordx4 v[60:63], v60, s[60:63], 0 offen sc0 sc1
	v_add_u32_e32 v44, 0xffff9fc0, v161
	buffer_load_dwordx4 v[4:7], v4, s[60:63], 0 offen sc0 sc1
	buffer_load_dwordx4 v[8:11], v8, s[60:63], 0 offen sc0 sc1
	buffer_load_dwordx4 v[28:31], v28, s[60:63], 0 offen sc0 sc1
	buffer_load_dwordx4 v[36:39], v36, s[60:63], 0 offen sc0 sc1
	buffer_load_dwordx4 v[44:47], v44, s[60:63], 0 offen sc0 sc1
	buffer_load_dwordx4 v[64:67], v64, s[60:63], 0 offen sc0 sc1
	s_waitcnt vmcnt(27)
	v_lshlrev_b32_e32 v114, 16, v68
	s_waitcnt vmcnt(26)
	v_lshlrev_b32_e32 v116, 16, v72
	v_and_b32_e32 v117, 0xffff0000, v72
	v_and_b32_e32 v115, 0xffff0000, v68
	s_waitcnt vmcnt(22)
	v_pk_mul_f32 v[182:183], v[110:111], v[116:117]
	v_lshlrev_b32_e32 v72, 16, v73
	v_pk_fma_f32 v[182:183], v[82:83], v[114:115], v[182:183] neg_lo:[0,0,1] neg_hi:[0,0,1]
	v_pk_mul_f32 v[114:115], v[110:111], v[114:115]
	v_and_b32_e32 v73, 0xffff0000, v73
	v_pk_fma_f32 v[114:115], v[82:83], v[116:117], v[114:115]
	v_lshlrev_b32_e32 v68, 16, v69
	v_and_b32_e32 v69, 0xffff0000, v69
	v_pk_mul_f32 v[116:117], v[112:113], v[72:73]
	v_lshlrev_b32_e32 v184, 16, v74
	v_pk_fma_f32 v[116:117], v[84:85], v[68:69], v[116:117] neg_lo:[0,0,1] neg_hi:[0,0,1]
	v_pk_mul_f32 v[68:69], v[112:113], v[68:69]
	v_and_b32_e32 v185, 0xffff0000, v74
	v_pk_fma_f32 v[68:69], v[84:85], v[72:73], v[68:69]
	v_pk_mul_f32 v[186:187], v[86:87], v[184:185]
	v_pk_mul_f32 v[72:73], v[68:69], s[88:89] op_sel_hi:[1,0]
	v_lshlrev_b32_e32 v68, 16, v70
	v_and_b32_e32 v69, 0xffff0000, v70
	v_pk_fma_f32 v[186:187], v[78:79], v[68:69], v[186:187] neg_lo:[0,0,1] neg_hi:[0,0,1]
	v_pk_mul_f32 v[68:69], v[86:87], v[68:69]
	v_lshlrev_b32_e32 v70, 16, v75
	v_pk_fma_f32 v[68:69], v[78:79], v[184:185], v[68:69]
	v_pk_mul_f32 v[182:183], v[182:183], s[88:89] op_sel_hi:[1,0]
	v_pk_mul_f32 v[184:185], v[68:69], s[88:89] op_sel_hi:[1,0]
	v_lshlrev_b32_e32 v68, 16, v71
	v_and_b32_e32 v69, 0xffff0000, v71
	v_and_b32_e32 v71, 0xffff0000, v75
	v_pk_mul_f32 v[74:75], v[88:89], v[70:71]
	v_pk_mul_f32 v[116:117], v[116:117], s[88:89] op_sel_hi:[1,0]
	v_pk_fma_f32 v[74:75], v[80:81], v[68:69], v[74:75] neg_lo:[0,0,1] neg_hi:[0,0,1]
	v_pk_mul_f32 v[68:69], v[88:89], v[68:69]
	v_pk_mul_f32 v[186:187], v[186:187], s[88:89] op_sel_hi:[1,0]
	v_pk_mul_f32 v[74:75], v[74:75], s[88:89] op_sel_hi:[1,0]
	v_pk_fma_f32 v[68:69], v[80:81], v[70:71], v[68:69]
	v_pk_mul_f32 v[114:115], v[114:115], s[88:89] op_sel_hi:[1,0]
	v_pk_mul_f32 v[188:189], v[68:69], s[88:89] op_sel_hi:[1,0]
	v_cvt_pk_bf16_f32 v68, v182, v183
	v_cvt_pk_bf16_f32 v69, v116, v117
	v_cvt_pk_bf16_f32 v70, v186, v187
	v_cvt_pk_bf16_f32 v71, v74, v75
	ds_write_b128 v118, v[68:71]
	v_cvt_pk_bf16_f32 v68, v114, v115
	v_cvt_pk_bf16_f32 v69, v72, v73
	v_cvt_pk_bf16_f32 v70, v184, v185
	v_cvt_pk_bf16_f32 v71, v188, v189
	ds_write_b128 v118, v[68:71] offset:64
	s_waitcnt vmcnt(21)
; #define LAS __attribute__((address_space(3)))
; #define LDS_WAIT() asm volatile("s_waitcnt lgkmcnt(0)" ::: "memory")
; __device__ __forceinline__ unsigned f2bf(float f) { return cvtpk(f, 0.f) & 0xffffu; }
; __device__ __forceinline__ u32x4 pack8u(const float* f) { u32x4 u; u.x = pk2(f[0], f[1]); u.y = pk2(f[2], f[3]); u.z = pk2(f[4], f[5]); u.w = pk2(f[6], f[7]); return u; }
; #define MFMA16(a, b, c) __builtin_amdgcn_mfma_f32_16x16x32_bf16((a), (b), (c), 0, 0, 0)
; __device__ __forceinline__ void ret_out_phase(int l, LAS unsigned char* lds, int wave, int lane_) {
;     ...
;             *(LAS u32x4*)(Qs + m * QP + 8 * part) = pack8u(o1); *(LAS u32x4*)(Qs + m * QP + 32 + 8 * part) = pack8u(o2);
;             rot8(src + 512, rot, pos, part, 1.0f, o1, o2);
;             *(LAS u32x4*)(Ks + m * QP + 8 * part) = pack8u(o1); *(LAS u32x4*)(Ks + m * QP + 32 + 8 * part) = pack8u(o2);
;             stage_vt(rawB, b, h, j, Vt, tid);
;         }
;         LDS_WAIT(); __syncthreads();
;         bf16x8 aq[2];
; #pragma unroll
;         for (int ks = 0; ks < 2; ++ks) aq[ks] = *(const LAS bf16x8*)(Qs + (16 * wave + fr) * QP + 32 * ks + 8 * fq);
; #pragma unroll
;         for (int nb = 0; nb < 8; ++nb) {
;             f32x4 sc = {0.f, 0.f, 0.f, 0.f};
; #pragma unroll
;             for (int ks = 0; ks < 2; ++ks) { const bf16x8 bk = *(const LAS bf16x8*)(Ks + (nb * 16 + fr) * QP + 32 * ks + 8 * fq); sc = MFMA16(aq[ks], bk, sc); }
; #pragma unroll
;             for (int i = 0; i < 4; ++i) { const int n = 16 * wave + 4 * fq + i, mk = nb * 16 + fr; const int d = n > mk ? n - mk : mk - n;
;                 Pw[(4 * fq + i) * KP + mk] = (bf16)f2bf(sc[i] * __builtin_amdgcn_exp2f(l2g * (float)d)); }
	v_lshlrev_b32_e32 v90, 16, v224
	s_waitcnt vmcnt(20)
	v_lshlrev_b32_e32 v114, 16, v228
	v_and_b32_e32 v115, 0xffff0000, v228
	v_and_b32_e32 v91, 0xffff0000, v224
	v_pk_mul_f32 v[116:117], v[110:111], v[114:115]
	v_lshlrev_b32_e32 v228, 16, v229
	v_pk_fma_f32 v[116:117], v[82:83], v[90:91], v[116:117] neg_lo:[0,0,1] neg_hi:[0,0,1]
	v_pk_mul_f32 v[82:83], v[82:83], v[114:115]
	v_and_b32_e32 v229, 0xffff0000, v229
	v_pk_fma_f32 v[82:83], v[110:111], v[90:91], v[82:83]
	v_lshlrev_b32_e32 v224, 16, v225
	v_and_b32_e32 v225, 0xffff0000, v225
	v_pk_mul_f32 v[90:91], v[112:113], v[228:229]
	v_pk_mul_f32 v[228:229], v[84:85], v[228:229]
	v_pk_fma_f32 v[90:91], v[84:85], v[224:225], v[90:91] neg_lo:[0,0,1] neg_hi:[0,0,1]
	v_lshlrev_b32_e32 v84, 16, v230
	v_and_b32_e32 v85, 0xffff0000, v230
	v_pk_fma_f32 v[228:229], v[112:113], v[224:225], v[228:229]
	v_lshlrev_b32_e32 v224, 16, v226
	v_and_b32_e32 v225, 0xffff0000, v226
	v_pk_mul_f32 v[110:111], v[86:87], v[84:85]
	v_lshlrev_b32_e32 v226, 16, v231
	v_pk_fma_f32 v[110:111], v[78:79], v[224:225], v[110:111] neg_lo:[0,0,1] neg_hi:[0,0,1]
	v_pk_mul_f32 v[78:79], v[78:79], v[84:85]
	v_mul_f32_e32 v84, 0xbfb8aa3b, v76
	v_pk_fma_f32 v[78:79], v[86:87], v[224:225], v[78:79]
	v_lshlrev_b32_e32 v224, 16, v227
	v_and_b32_e32 v225, 0xffff0000, v227
	v_and_b32_e32 v227, 0xffff0000, v231
	v_pk_mul_f32 v[230:231], v[88:89], v[226:227]
	v_pk_mul_f32 v[226:227], v[80:81], v[226:227]
	v_pk_fma_f32 v[230:231], v[80:81], v[224:225], v[230:231] neg_lo:[0,0,1] neg_hi:[0,0,1]
	v_pk_fma_f32 v[80:81], v[88:89], v[224:225], v[226:227]
	v_cvt_pk_bf16_f32 v224, v116, v117
	v_cvt_pk_bf16_f32 v225, v90, v91
	v_cvt_pk_bf16_f32 v226, v110, v111
	v_cvt_pk_bf16_f32 v227, v230, v231
	ds_write_b128 v118, v[224:227] offset:18432
	v_cvt_pk_bf16_f32 v224, v82, v83
	v_cvt_pk_bf16_f32 v225, v228, v229
	v_cvt_pk_bf16_f32 v226, v78, v79
	v_cvt_pk_bf16_f32 v227, v80, v81
	ds_write_b128 v118, v[224:227] offset:18496
	s_waitcnt vmcnt(19)
	ds_write_b16 v119, v232 offset:36864
	ds_write_b16_d16_hi v119, v232 offset:37136
	ds_write_b16 v119, v233 offset:37408
	ds_write_b16_d16_hi v119, v233 offset:37680
	ds_write_b16 v119, v234 offset:37952
	ds_write_b16_d16_hi v119, v234 offset:38224
	ds_write_b16 v119, v235 offset:38496
	ds_write_b16_d16_hi v119, v235 offset:38768
	s_waitcnt vmcnt(18)
	ds_write_b16 v119, v236 offset:39040
	ds_write_b16_d16_hi v119, v236 offset:39312
	ds_write_b16 v119, v237 offset:39584
	ds_write_b16_d16_hi v119, v237 offset:39856
	ds_write_b16 v119, v238 offset:40128
	ds_write_b16_d16_hi v119, v238 offset:40400
	ds_write_b16 v119, v239 offset:40672
	ds_write_b16_d16_hi v119, v239 offset:40944
	s_waitcnt vmcnt(17)
	ds_write_b16 v119, v240 offset:41216
	ds_write_b16_d16_hi v119, v240 offset:41488
	ds_write_b16 v119, v241 offset:41760
	ds_write_b16_d16_hi v119, v241 offset:42032
	ds_write_b16 v119, v242 offset:42304
	ds_write_b16_d16_hi v119, v242 offset:42576
	ds_write_b16 v119, v243 offset:42848
	ds_write_b16_d16_hi v119, v243 offset:43120
	s_waitcnt vmcnt(16)
	ds_write_b16 v119, v244 offset:43392
	ds_write_b16_d16_hi v119, v244 offset:43664
	ds_write_b16 v119, v245 offset:43936
	ds_write_b16_d16_hi v119, v245 offset:44208
	ds_write_b16 v119, v246 offset:44480
	ds_write_b16_d16_hi v119, v246 offset:44752
	ds_write_b16 v119, v247 offset:45024
	ds_write_b16_d16_hi v119, v247 offset:45296
	s_waitcnt lgkmcnt(0)
	s_waitcnt lgkmcnt(0)
	s_barrier
	ds_read_b128 v[72:75], v162
	ds_read_b128 v[68:71], v162 offset:64
	ds_read_b128 v[76:79], v163 offset:18432
	ds_read_b128 v[80:83], v163 offset:18496
	s_waitcnt lgkmcnt(1)
	v_mfma_f32_16x16x32_bf16 v[76:79], v[72:75], v[76:79], 0
	v_add_u32_e32 v109, 0xffffa7c0, v161
	s_waitcnt lgkmcnt(0)
	v_mfma_f32_16x16x32_bf16 v[76:79], v[68:71], v[80:83], v[76:79]
	v_mul_f32_e32 v80, v84, v121
	v_exp_f32_e32 v80, v80
	s_waitcnt vmcnt(0)
	v_mfma_f32_16x16x32_bf16 v[4:7], v[72:75], v[4:7], 0
	v_mfma_f32_16x16x32_bf16 v[8:11], v[72:75], v[8:11], 0
	s_nop 3
	v_mul_f32_e32 v76, v80, v76
	v_cvt_pk_bf16_f32 v76, v76, s0
	ds_write_b16 v167, v76
	v_mul_f32_e32 v76, v84, v122
	v_exp_f32_e32 v76, v76
	v_mfma_f32_16x16x32_bf16 v[4:7], v[68:71], v[16:19], v[4:7]
	v_mul_f32_e32 v76, v76, v77
	v_cvt_pk_bf16_f32 v76, v76, s0
	ds_write_b16 v167, v76 offset:272
	v_mul_f32_e32 v76, v84, v123
	v_exp_f32_e32 v76, v76
	v_mfma_f32_16x16x32_bf16 v[16:19], v[68:71], v[24:27], v[8:11]
	v_mul_f32_e32 v76, v76, v78
	v_cvt_pk_bf16_f32 v76, v76, s0
	ds_write_b16 v167, v76 offset:544
	v_mul_f32_e32 v76, v84, v124
	v_exp_f32_e32 v76, v76
	v_mfma_f32_16x16x32_bf16 v[10:13], v[72:75], v[12:15], 0
	v_mul_f32_e32 v76, v76, v79
	v_cvt_pk_bf16_f32 v76, v76, s0
	ds_write_b16 v167, v76 offset:816
	ds_read_b128 v[76:79], v163 offset:20736
	ds_read_b128 v[80:83], v163 offset:20800
	s_waitcnt lgkmcnt(1)
	v_mfma_f32_16x16x32_bf16 v[76:79], v[72:75], v[76:79], 0
	s_waitcnt lgkmcnt(0)
	v_mfma_f32_16x16x32_bf16 v[76:79], v[68:71], v[80:83], v[76:79]
	v_mul_f32_e32 v80, v84, v125
	v_exp_f32_e32 v80, v80
	v_mfma_f32_16x16x32_bf16 v[10:13], v[68:71], v[32:35], v[10:13]
	s_nop 4
	v_mul_f32_e32 v76, v80, v76
	v_cvt_pk_bf16_f32 v76, v76, s0
	ds_write_b16 v167, v76 offset:32
	v_mul_f32_e32 v76, v84, v126
	v_exp_f32_e32 v76, v76
	s_nop 0
	v_mul_f32_e32 v76, v76, v77
	v_cvt_pk_bf16_f32 v76, v76, s0
	ds_write_b16 v167, v76 offset:304
	v_mul_f32_e32 v76, v84, v127
	v_exp_f32_e32 v76, v76
	s_nop 0
	v_mul_f32_e32 v76, v76, v78
	v_cvt_pk_bf16_f32 v76, v76, s0
	ds_write_b16 v167, v76 offset:576
	v_mul_f32_e32 v76, v84, v128
	v_exp_f32_e32 v76, v76
	s_nop 0
	v_mul_f32_e32 v76, v76, v79
	v_cvt_pk_bf16_f32 v76, v76, s0
	ds_write_b16 v167, v76 offset:848
	ds_read_b128 v[76:79], v163 offset:23040
	ds_read_b128 v[80:83], v163 offset:23104
	s_waitcnt lgkmcnt(1)
; #define LAS __attribute__((address_space(3)))
; #define LDS_WAIT() asm volatile("s_waitcnt lgkmcnt(0)" ::: "memory")
; __device__ __forceinline__ unsigned f2bf(float f) { return cvtpk(f, 0.f) & 0xffffu; }
; #define MFMA16(a, b, c) __builtin_amdgcn_mfma_f32_16x16x32_bf16((a), (b), (c), 0, 0, 0)
; __device__ __forceinline__ void ret_out_phase(int l, LAS unsigned char* lds, int wave, int lane_) {
;     ...
;         for (int nb = 0; nb < 8; ++nb) {
;             f32x4 sc = {0.f, 0.f, 0.f, 0.f};
; #pragma unroll
;             for (int ks = 0; ks < 2; ++ks) { const bf16x8 bk = *(const LAS bf16x8*)(Ks + (nb * 16 + fr) * QP + 32 * ks + 8 * fq); sc = MFMA16(aq[ks], bk, sc); }
; #pragma unroll
;             for (int i = 0; i < 4; ++i) { const int n = 16 * wave + 4 * fq + i, mk = nb * 16 + fr; const int d = n > mk ? n - mk : mk - n;
;                 Pw[(4 * fq + i) * KP + mk] = (bf16)f2bf(sc[i] * __builtin_amdgcn_exp2f(l2g * (float)d)); }
;         }
;         LDS_WAIT(); asm volatile("" ::: "memory");
;         f32x4 y1[8];
;         f32x4 xfv, xbv;
; #pragma unroll
;         for (int i = 0; i < 4; ++i) { const int nl = 16 * wave + 4 * fq + i; xfv[i] = __builtin_amdgcn_exp2f(l2g * (float)(nl + 1)); xbv[i] = __builtin_amdgcn_exp2f(l2g * (float)(RC - nl)); }
	v_mfma_f32_16x16x32_bf16 v[76:79], v[72:75], v[76:79], 0
	s_waitcnt lgkmcnt(0)
	v_mfma_f32_16x16x32_bf16 v[76:79], v[68:71], v[80:83], v[76:79]
	v_mul_f32_e32 v80, v84, v129
	v_exp_f32_e32 v80, v80
	s_nop 5
	v_mul_f32_e32 v76, v80, v76
	v_cvt_pk_bf16_f32 v76, v76, s0
	ds_write_b16 v167, v76 offset:64
	v_mul_f32_e32 v76, v84, v130
	v_exp_f32_e32 v76, v76
	s_nop 0
	v_mul_f32_e32 v76, v76, v77
	v_cvt_pk_bf16_f32 v76, v76, s0
	ds_write_b16 v167, v76 offset:336
	v_mul_f32_e32 v76, v84, v131
	v_exp_f32_e32 v76, v76
	s_nop 0
	v_mul_f32_e32 v76, v76, v78
	v_cvt_pk_bf16_f32 v76, v76, s0
	ds_write_b16 v167, v76 offset:608
	v_mul_f32_e32 v76, v84, v132
	v_exp_f32_e32 v76, v76
	s_nop 0
	v_mul_f32_e32 v76, v76, v79
	v_cvt_pk_bf16_f32 v76, v76, s0
	ds_write_b16 v167, v76 offset:880
	ds_read_b128 v[76:79], v163 offset:25344
	ds_read_b128 v[80:83], v163 offset:25408
	s_waitcnt lgkmcnt(1)
	v_mfma_f32_16x16x32_bf16 v[76:79], v[72:75], v[76:79], 0
	s_waitcnt lgkmcnt(0)
	v_mfma_f32_16x16x32_bf16 v[76:79], v[68:71], v[80:83], v[76:79]
	v_mul_f32_e32 v80, v84, v133
	v_exp_f32_e32 v80, v80
	s_nop 5
	v_mul_f32_e32 v76, v80, v76
	v_cvt_pk_bf16_f32 v76, v76, s0
	ds_write_b16 v167, v76 offset:96
	v_mul_f32_e32 v76, v84, v134
	v_exp_f32_e32 v76, v76
	s_nop 0
	v_mul_f32_e32 v76, v76, v77
	v_cvt_pk_bf16_f32 v76, v76, s0
	ds_write_b16 v167, v76 offset:368
	v_mul_f32_e32 v76, v84, v135
	v_exp_f32_e32 v76, v76
	s_nop 0
	v_mul_f32_e32 v76, v76, v78
	v_cvt_pk_bf16_f32 v76, v76, s0
	ds_write_b16 v167, v76 offset:640
	v_mul_f32_e32 v76, v84, v136
	v_exp_f32_e32 v76, v76
	s_nop 0
	v_mul_f32_e32 v76, v76, v79
	v_cvt_pk_bf16_f32 v76, v76, s0
	ds_write_b16 v167, v76 offset:912
	ds_read_b128 v[76:79], v163 offset:27648
	ds_read_b128 v[80:83], v163 offset:27712
	s_waitcnt lgkmcnt(1)
	v_mfma_f32_16x16x32_bf16 v[76:79], v[72:75], v[76:79], 0
	s_waitcnt lgkmcnt(0)
	v_mfma_f32_16x16x32_bf16 v[76:79], v[68:71], v[80:83], v[76:79]
	v_mul_f32_e32 v80, v84, v137
	v_exp_f32_e32 v80, v80
	s_nop 5
	v_mul_f32_e32 v76, v80, v76
	v_cvt_pk_bf16_f32 v76, v76, s0
	ds_write_b16 v167, v76 offset:128
	v_mul_f32_e32 v76, v84, v138
	v_exp_f32_e32 v76, v76
	s_nop 0
	v_mul_f32_e32 v76, v76, v77
	v_cvt_pk_bf16_f32 v76, v76, s0
	ds_write_b16 v167, v76 offset:400
	v_mul_f32_e32 v76, v84, v139
	v_exp_f32_e32 v76, v76
	s_nop 0
	v_mul_f32_e32 v76, v76, v78
	v_cvt_pk_bf16_f32 v76, v76, s0
	ds_write_b16 v167, v76 offset:672
	v_mul_f32_e32 v76, v84, v140
	v_exp_f32_e32 v76, v76
	s_nop 0
	v_mul_f32_e32 v76, v76, v79
	v_cvt_pk_bf16_f32 v76, v76, s0
	ds_write_b16 v167, v76 offset:944
	ds_read_b128 v[76:79], v163 offset:29952
	ds_read_b128 v[80:83], v163 offset:30016
	s_waitcnt lgkmcnt(1)
	v_mfma_f32_16x16x32_bf16 v[76:79], v[72:75], v[76:79], 0
	s_waitcnt lgkmcnt(0)
	v_mfma_f32_16x16x32_bf16 v[76:79], v[68:71], v[80:83], v[76:79]
	v_mul_f32_e32 v80, v84, v141
	v_exp_f32_e32 v80, v80
	s_nop 5
	v_mul_f32_e32 v76, v80, v76
	v_cvt_pk_bf16_f32 v76, v76, s0
	ds_write_b16 v167, v76 offset:160
	v_mul_f32_e32 v76, v84, v142
	v_exp_f32_e32 v76, v76
	s_nop 0
	v_mul_f32_e32 v76, v76, v77
	v_cvt_pk_bf16_f32 v76, v76, s0
	ds_write_b16 v167, v76 offset:432
	v_mul_f32_e32 v76, v84, v143
	v_exp_f32_e32 v76, v76
	s_nop 0
	v_mul_f32_e32 v76, v76, v78
	v_cvt_pk_bf16_f32 v76, v76, s0
	ds_write_b16 v167, v76 offset:704
	v_mul_f32_e32 v76, v84, v144
	v_exp_f32_e32 v76, v76
	s_nop 0
	v_mul_f32_e32 v76, v76, v79
	v_cvt_pk_bf16_f32 v76, v76, s0
	ds_write_b16 v167, v76 offset:976
	ds_read_b128 v[76:79], v163 offset:32256
	ds_read_b128 v[80:83], v163 offset:32320
	s_waitcnt lgkmcnt(1)
	v_mfma_f32_16x16x32_bf16 v[76:79], v[72:75], v[76:79], 0
	s_waitcnt lgkmcnt(0)
	v_mfma_f32_16x16x32_bf16 v[76:79], v[68:71], v[80:83], v[76:79]
	v_mul_f32_e32 v80, v84, v145
	v_exp_f32_e32 v80, v80
	s_nop 5
	v_mul_f32_e32 v76, v80, v76
	v_cvt_pk_bf16_f32 v76, v76, s0
	ds_write_b16 v167, v76 offset:192
	v_mul_f32_e32 v76, v84, v146
	v_exp_f32_e32 v76, v76
	s_nop 0
	v_mul_f32_e32 v76, v76, v77
	v_cvt_pk_bf16_f32 v76, v76, s0
	ds_write_b16 v167, v76 offset:464
	v_mul_f32_e32 v76, v84, v147
	v_exp_f32_e32 v76, v76
	s_nop 0
	v_mul_f32_e32 v76, v76, v78
	v_cvt_pk_bf16_f32 v76, v76, s0
	ds_write_b16 v167, v76 offset:736
	v_mul_f32_e32 v76, v84, v148
	v_exp_f32_e32 v76, v76
	s_nop 0
	v_mul_f32_e32 v76, v76, v79
	v_cvt_pk_bf16_f32 v76, v76, s0
	ds_write_b16 v167, v76 offset:1008
	ds_read_b128 v[76:79], v163 offset:34560
	ds_read_b128 v[80:83], v163 offset:34624
	s_waitcnt lgkmcnt(1)
	v_mfma_f32_16x16x32_bf16 v[76:79], v[72:75], v[76:79], 0
	s_waitcnt lgkmcnt(0)
	v_mfma_f32_16x16x32_bf16 v[76:79], v[68:71], v[80:83], v[76:79]
	v_mul_f32_e32 v80, v84, v149
	v_exp_f32_e32 v80, v80
	s_nop 5
	v_mul_f32_e32 v76, v80, v76
	v_cvt_pk_bf16_f32 v76, v76, s0
	ds_write_b16 v167, v76 offset:224
	v_mul_f32_e32 v76, v84, v150
	v_exp_f32_e32 v76, v76
	s_nop 0
	v_mul_f32_e32 v76, v76, v77
	v_cvt_pk_bf16_f32 v76, v76, s0
	ds_write_b16 v167, v76 offset:496
	v_mul_f32_e32 v76, v84, v151
	v_exp_f32_e32 v76, v76
	s_nop 0
	v_mul_f32_e32 v76, v76, v78
	v_cvt_pk_bf16_f32 v76, v76, s0
	ds_write_b16 v167, v76 offset:768
	v_mul_f32_e32 v76, v84, v152
	v_exp_f32_e32 v76, v76
	s_nop 0
	v_mul_f32_e32 v76, v76, v79
	v_cvt_pk_bf16_f32 v76, v76, s0
	ds_write_b16 v167, v76 offset:1040
	v_mul_f32_e32 v76, v84, v153
	v_exp_f32_e32 v112, v76
	v_mul_f32_e32 v76, v84, v154
	v_exp_f32_e32 v110, v76
	v_mul_f32_e32 v76, v84, v155
	v_exp_f32_e32 v113, v76
	v_mul_f32_e32 v76, v84, v156
	v_exp_f32_e32 v111, v76
	v_mul_f32_e32 v76, v84, v157
	v_exp_f32_e32 v116, v76
	v_mul_f32_e32 v76, v84, v158
	v_exp_f32_e32 v114, v76
	v_mul_f32_e32 v76, v84, v159
	s_waitcnt lgkmcnt(0)
; #define LAS __attribute__((address_space(3)))
; #define MFMA16(a, b, c) __builtin_amdgcn_mfma_f32_16x16x32_bf16((a), (b), (c), 0, 0, 0)
; __device__ __forceinline__ void ret_out_phase(int l, LAS unsigned char* lds, int wave, int lane_) {
;     ...
;         bf16x8 ap[4];
; #pragma unroll
;         for (int ks = 0; ks < 4; ++ks) ap[ks] = *(const LAS bf16x8*)(Pw + fr * KP + 32 * ks + 8 * fq);
; #pragma unroll
;         for (int g = 0; g < 2; ++g) {
;             if (g == 1) { RET_LD_STATES(1); }
; #pragma unroll
;             for (int o4 = 0; o4 < 4; ++o4) {
;                 const int ob = 4 * g + o4;
;                 f32x4 y2 = {0.f, 0.f, 0.f, 0.f}, y3 = y2; y1[ob] = y2;
; #pragma unroll
;                 for (int ks = 0; ks < 4; ++ks) { const bf16x8 bvv = *(const LAS bf16x8*)(Vt + (ob * 16 + fr) * KP + 32 * ks + 8 * fq); y1[ob] = MFMA16(ap[ks], bvv, y1[ob]); }
; #pragma unroll
;                 for (int ks = 0; ks < 2; ++ks) { y2 = MFMA16(aq[ks], __builtin_bit_cast(bf16x8, sfv[o4][ks]), y2); y3 = MFMA16(aq[ks], __builtin_bit_cast(bf16x8, sbv[o4][ks]), y3); }
;                 y1[ob] = y1[ob] + xfv * y2 + xbv * y3;
;             }
	v_exp_f32_e32 v117, v76
	v_mul_f32_e32 v76, v84, v160
	v_exp_f32_e32 v115, v76
	v_add_u32_e32 v76, v120, v93
	ds_read_b128 v[88:91], v76
	ds_read_b128 v[84:87], v76 offset:64
	ds_read_b128 v[80:83], v76 offset:128
	ds_read_b128 v[76:79], v76 offset:192
	ds_read_b128 v[182:185], v168 offset:36864
	ds_read_b128 v[186:189], v168 offset:36928
	s_waitcnt lgkmcnt(1)
	v_mfma_f32_16x16x32_bf16 v[182:185], v[88:91], v[182:185], 0
	s_waitcnt lgkmcnt(0)
	v_mfma_f32_16x16x32_bf16 v[182:185], v[84:87], v[186:189], v[182:185]
	ds_read_b128 v[186:189], v168 offset:36992
	s_waitcnt lgkmcnt(0)
	v_mfma_f32_16x16x32_bf16 v[182:185], v[80:83], v[186:189], v[182:185]
	ds_read_b128 v[186:189], v168 offset:37056
	s_waitcnt lgkmcnt(0)
	v_mfma_f32_16x16x32_bf16 v[182:185], v[76:79], v[186:189], v[182:185]
	s_nop 7
	v_pk_fma_f32 v[6:7], v[116:117], v[6:7], v[184:185]
	v_pk_fma_f32 v[4:5], v[112:113], v[4:5], v[182:183]
	v_pk_fma_f32 v[8:9], v[114:115], v[18:19], v[6:7]
	v_pk_fma_f32 v[24:25], v[110:111], v[16:17], v[4:5]
	ds_read_b128 v[4:7], v180 offset:36864
	ds_read_b128 v[16:19], v180 offset:36928
	s_waitcnt lgkmcnt(1)
	v_mfma_f32_16x16x32_bf16 v[4:7], v[88:91], v[4:7], 0
	s_waitcnt lgkmcnt(0)
	v_mfma_f32_16x16x32_bf16 v[4:7], v[84:87], v[16:19], v[4:7]
	ds_read_b128 v[16:19], v180 offset:36992
	s_waitcnt lgkmcnt(0)
	v_mfma_f32_16x16x32_bf16 v[4:7], v[80:83], v[16:19], v[4:7]
	ds_read_b128 v[16:19], v180 offset:37056
	s_waitcnt lgkmcnt(0)
	v_mfma_f32_16x16x32_bf16 v[4:7], v[76:79], v[16:19], v[4:7]
	v_mfma_f32_16x16x32_bf16 v[14:17], v[72:75], v[20:23], 0
	s_nop 6
	v_fma_f32 v6, v116, v12, v6
	v_fma_f32 v7, v117, v13, v7
	v_pk_fma_f32 v[4:5], v[112:113], v[10:11], v[4:5]
	v_mfma_f32_16x16x32_bf16 v[14:17], v[68:71], v[40:43], v[14:17]
	s_nop 7
	v_pk_fma_f32 v[10:11], v[114:115], v[16:17], v[6:7]
	v_pk_fma_f32 v[22:23], v[110:111], v[14:15], v[4:5]
	ds_read_b128 v[4:7], v180 offset:41216
	ds_read_b128 v[12:15], v180 offset:41280
	s_waitcnt lgkmcnt(1)
	v_mfma_f32_16x16x32_bf16 v[4:7], v[88:91], v[4:7], 0
	s_waitcnt lgkmcnt(0)
	v_mfma_f32_16x16x32_bf16 v[4:7], v[84:87], v[12:15], v[4:7]
	ds_read_b128 v[12:15], v180 offset:41344
	s_waitcnt lgkmcnt(0)
	v_mfma_f32_16x16x32_bf16 v[4:7], v[80:83], v[12:15], v[4:7]
	ds_read_b128 v[12:15], v180 offset:41408
	s_waitcnt lgkmcnt(0)
	v_mfma_f32_16x16x32_bf16 v[4:7], v[76:79], v[12:15], v[4:7]
	v_mfma_f32_16x16x32_bf16 v[12:15], v[72:75], v[28:31], 0
	v_mfma_f32_16x16x32_bf16 v[16:19], v[72:75], v[36:39], 0
	v_mfma_f32_16x16x32_bf16 v[12:15], v[68:71], v[48:51], v[12:15]
	v_mfma_f32_16x16x32_bf16 v[16:19], v[68:71], v[56:59], v[16:19]
	s_nop 6
	v_fma_f32 v6, v116, v14, v6
	v_fma_f32 v7, v117, v15, v7
	v_pk_fma_f32 v[4:5], v[112:113], v[12:13], v[4:5]
	v_pk_fma_f32 v[12:13], v[114:115], v[18:19], v[6:7]
	v_pk_fma_f32 v[26:27], v[110:111], v[16:17], v[4:5]
	ds_read_b128 v[4:7], v180 offset:45568
	ds_read_b128 v[14:17], v180 offset:45632
	s_waitcnt lgkmcnt(1)
	v_mfma_f32_16x16x32_bf16 v[4:7], v[88:91], v[4:7], 0
	s_waitcnt lgkmcnt(0)
	v_mfma_f32_16x16x32_bf16 v[4:7], v[84:87], v[14:17], v[4:7]
	ds_read_b128 v[14:17], v180 offset:45696
	s_waitcnt lgkmcnt(0)
	v_mfma_f32_16x16x32_bf16 v[4:7], v[80:83], v[14:17], v[4:7]
	ds_read_b128 v[14:17], v180 offset:45760
	s_waitcnt lgkmcnt(0)
	v_mfma_f32_16x16x32_bf16 v[4:7], v[76:79], v[14:17], v[4:7]
	v_mfma_f32_16x16x32_bf16 v[14:17], v[72:75], v[44:47], 0
	v_mfma_f32_16x16x32_bf16 v[18:21], v[72:75], v[52:55], 0
	v_mfma_f32_16x16x32_bf16 v[14:17], v[68:71], v[60:63], v[14:17]
	v_mfma_f32_16x16x32_bf16 v[18:21], v[68:71], v[64:67], v[18:21]
	s_nop 6
	v_fma_f32 v6, v116, v16, v6
	v_fma_f32 v7, v117, v17, v7
	v_pk_fma_f32 v[4:5], v[112:113], v[14:15], v[4:5]
	v_add_u32_e32 v16, 0xffffc000, v161
	v_pk_fma_f32 v[14:15], v[114:115], v[20:21], v[6:7]
	v_pk_fma_f32 v[28:29], v[110:111], v[18:19], v[4:5]
	buffer_load_dwordx4 v[4:7], v161, s[60:63], 0 offen sc0 sc1
	buffer_load_dwordx4 v[38:41], v16, s[60:63], 0 offen sc0 sc1
	v_add_u32_e32 v16, 0xffffbfc0, v161
	v_subrev_u32_e32 v17, 64, v161
	buffer_load_dwordx4 v[42:45], v17, s[60:63], 0 offen sc0 sc1
	buffer_load_dwordx4 v[46:49], v16, s[60:63], 0 offen sc0 sc1
	v_add_u32_e32 v16, 0xfffff800, v161
	buffer_load_dwordx4 v[50:53], v16, s[60:63], 0 offen sc0 sc1
	v_add_u32_e32 v16, 0xffffb800, v161
	buffer_load_dwordx4 v[54:57], v16, s[60:63], 0 offen sc0 sc1
	v_add_u32_e32 v16, 0xffffb7c0, v161
	v_add_u32_e32 v17, 0xfffff7c0, v161
	buffer_load_dwordx4 v[58:61], v17, s[60:63], 0 offen sc0 sc1
	buffer_load_dwordx4 v[62:65], v16, s[60:63], 0 offen sc0 sc1
	v_add_u32_e32 v16, 0xfffff000, v161
	buffer_load_dwordx4 v[18:21], v16, s[60:63], 0 offen sc0 sc1
	v_add_u32_e32 v16, 0xffffb000, v161
	buffer_load_dwordx4 v[34:37], v16, s[60:63], 0 offen sc0 sc1
	v_add_u32_e32 v16, 0xffffafc0, v161
	v_add_u32_e32 v17, 0xffffefc0, v161
	buffer_load_dwordx4 v[182:185], v17, s[60:63], 0 offen sc0 sc1
	buffer_load_dwordx4 v[186:189], v16, s[60:63], 0 offen sc0 sc1
	v_add_u32_e32 v16, 0xffffe800, v161
	buffer_load_dwordx4 v[30:33], v16, s[60:63], 0 offen sc0 sc1
	v_add_u32_e32 v16, 0xffffa800, v161
	buffer_load_dwordx4 v[190:193], v16, s[60:63], 0 offen sc0 sc1
	v_add_u32_e32 v16, 0xffffe7c0, v161
	buffer_load_dwordx4 v[194:197], v16, s[60:63], 0 offen sc0 sc1
	buffer_load_dwordx4 v[208:211], v109, s[60:63], 0 offen sc0 sc1
	ds_read_b128 v[212:215], v180 offset:49920
	ds_read_b128 v[216:219], v180 offset:49984
	s_waitcnt lgkmcnt(1)
	v_mfma_f32_16x16x32_bf16 v[212:215], v[88:91], v[212:215], 0
	v_add_u32_e32 v161, s27, v161
	s_waitcnt lgkmcnt(0)
	v_mfma_f32_16x16x32_bf16 v[212:215], v[84:87], v[216:219], v[212:215]
	ds_read_b128 v[216:219], v180 offset:50048
	s_waitcnt vmcnt(1)
; #define LAS __attribute__((address_space(3)))
; #define MFMA16(a, b, c) __builtin_amdgcn_mfma_f32_16x16x32_bf16((a), (b), (c), 0, 0, 0)
; __device__ __forceinline__ void ret_out_phase(int l, LAS unsigned char* lds, int wave, int lane_) {
;     ...
;                 for (int ks = 0; ks < 4; ++ks) { const bf16x8 bvv = *(const LAS bf16x8*)(Vt + (ob * 16 + fr) * KP + 32 * ks + 8 * fq); y1[ob] = MFMA16(ap[ks], bvv, y1[ob]); }
; #pragma unroll
;                 for (int ks = 0; ks < 2; ++ks) { y2 = MFMA16(aq[ks], __builtin_bit_cast(bf16x8, sfv[o4][ks]), y2); y3 = MFMA16(aq[ks], __builtin_bit_cast(bf16x8, sbv[o4][ks]), y3); }
;                 y1[ob] = y1[ob] + xfv * y2 + xbv * y3;
;             }
;             asm volatile("" ::: "memory");
;         }
; #pragma unroll
;         for (int i = 0; i < 4; ++i) {
;             const int nl = 16 * wave + 4 * fq + i;
;             float v[8]; float s = 0.f;
; #pragma unroll
;             for (int ob = 0; ob < 8; ++ob) { v[ob] = y1[ob][i]; s += v[ob]; }
;             s += __shfl_xor(s, 1); s += __shfl_xor(s, 2); s += __shfl_xor(s, 4); s += __shfl_xor(s, 8);
	v_mfma_f32_16x16x32_bf16 v[194:197], v[72:75], v[194:197], 0
	v_mfma_f32_16x16x32_bf16 v[30:33], v[68:71], v[30:33], v[194:197]
	s_nop 6
	ds_read_b128 v[194:197], v180 offset:54336
	s_waitcnt lgkmcnt(1)
	v_mfma_f32_16x16x32_bf16 v[212:215], v[80:83], v[216:219], v[212:215]
	ds_read_b128 v[216:219], v180 offset:50112
	s_waitcnt vmcnt(0)
	v_mfma_f32_16x16x32_bf16 v[208:211], v[72:75], v[208:211], 0
	v_mfma_f32_16x16x32_bf16 v[186:189], v[72:75], v[186:189], 0
	v_mfma_f32_16x16x32_bf16 v[190:193], v[68:71], v[190:193], v[208:211]
	v_mfma_f32_16x16x32_bf16 v[34:37], v[68:71], v[34:37], v[186:189]
	s_nop 5
	ds_read_b128 v[186:189], v180 offset:58688
	s_waitcnt lgkmcnt(1)
	v_mfma_f32_16x16x32_bf16 v[212:215], v[76:79], v[216:219], v[212:215]
	v_mfma_f32_16x16x32_bf16 v[182:185], v[72:75], v[182:185], 0
	v_mfma_f32_16x16x32_bf16 v[182:185], v[68:71], v[18:21], v[182:185]
	s_nop 5
	v_fma_f32 v16, v116, v192, v214
	v_fma_f32 v17, v117, v193, v215
	v_pk_fma_f32 v[66:67], v[112:113], v[190:191], v[212:213]
	ds_read_b128 v[190:193], v180 offset:54272
	s_waitcnt lgkmcnt(0)
	v_mfma_f32_16x16x32_bf16 v[190:193], v[88:91], v[190:193], 0
	v_fma_f32 v16, v114, v32, v16
	v_fma_f32 v17, v115, v33, v17
	v_pk_fma_f32 v[32:33], v[110:111], v[30:31], v[66:67]
	v_mfma_f32_16x16x32_bf16 v[190:193], v[84:87], v[194:197], v[190:193]
	ds_read_b128 v[194:197], v180 offset:54400
	s_waitcnt lgkmcnt(0)
	v_mfma_f32_16x16x32_bf16 v[190:193], v[80:83], v[194:197], v[190:193]
	ds_read_b128 v[194:197], v180 offset:54464
	s_waitcnt lgkmcnt(0)
	v_mfma_f32_16x16x32_bf16 v[190:193], v[76:79], v[194:197], v[190:193]
	v_mfma_f32_16x16x32_bf16 v[62:65], v[72:75], v[62:65], 0
	s_nop 6
	v_fma_f32 v18, v116, v36, v192
	v_fma_f32 v19, v117, v37, v193
	v_pk_fma_f32 v[20:21], v[112:113], v[34:35], v[190:191]
	v_pk_fma_f32 v[18:19], v[114:115], v[184:185], v[18:19]
	v_pk_fma_f32 v[34:35], v[110:111], v[182:183], v[20:21]
	ds_read_b128 v[182:185], v180 offset:58624
	s_waitcnt lgkmcnt(0)
	v_mfma_f32_16x16x32_bf16 v[182:185], v[88:91], v[182:185], 0
	v_mfma_f32_16x16x32_bf16 v[182:185], v[84:87], v[186:189], v[182:185]
	ds_read_b128 v[186:189], v180 offset:58752
	s_waitcnt lgkmcnt(0)
	v_mfma_f32_16x16x32_bf16 v[182:185], v[80:83], v[186:189], v[182:185]
	ds_read_b128 v[186:189], v180 offset:58816
	v_mfma_f32_16x16x32_bf16 v[58:61], v[72:75], v[58:61], 0
	s_waitcnt lgkmcnt(0)
	v_mfma_f32_16x16x32_bf16 v[182:185], v[76:79], v[186:189], v[182:185]
	v_mfma_f32_16x16x32_bf16 v[54:57], v[68:71], v[54:57], v[62:65]
	v_mfma_f32_16x16x32_bf16 v[50:53], v[68:71], v[50:53], v[58:61]
	v_mfma_f32_16x16x32_bf16 v[46:49], v[72:75], v[46:49], 0
	s_nop 5
	v_fma_f32 v20, v116, v56, v184
	v_fma_f32 v21, v117, v57, v185
	v_pk_fma_f32 v[30:31], v[112:113], v[54:55], v[182:183]
	v_pk_fma_f32 v[20:21], v[114:115], v[52:53], v[20:21]
	v_pk_fma_f32 v[36:37], v[110:111], v[50:51], v[30:31]
	ds_read_b128 v[50:53], v180 offset:62976
	ds_read_b128 v[54:57], v180 offset:63040
	s_waitcnt lgkmcnt(1)
	v_mfma_f32_16x16x32_bf16 v[50:53], v[88:91], v[50:53], 0
	v_mov_b32_e32 v61, v36
	s_waitcnt lgkmcnt(0)
	v_mfma_f32_16x16x32_bf16 v[50:53], v[84:87], v[54:57], v[50:53]
	ds_read_b128 v[54:57], v180 offset:63104
	s_waitcnt lgkmcnt(0)
	v_mfma_f32_16x16x32_bf16 v[50:53], v[80:83], v[54:57], v[50:53]
	ds_read_b128 v[54:57], v180 offset:63168
	s_load_dwordx2 s[48:49], s[30:31], 0x90
	v_mfma_f32_16x16x32_bf16 v[42:45], v[72:75], v[42:45], 0
	s_waitcnt lgkmcnt(0)
	s_add_u32 s43, s48, s26
	v_mfma_f32_16x16x32_bf16 v[50:53], v[76:79], v[54:57], v[50:53]
	s_addc_u32 s47, s49, 0
	s_lshl_b32 s42, s42, 9
	s_add_u32 s42, s43, s42
	v_mfma_f32_16x16x32_bf16 v[38:41], v[68:71], v[38:41], v[46:49]
	s_addc_u32 s43, s47, 0
	s_add_i32 s46, s46, s58
	s_add_i32 s29, s29, s28
	v_mfma_f32_16x16x32_bf16 v[4:7], v[68:71], v[4:7], v[42:45]
	s_cmpk_lt_i32 s46, 0x800
	s_nop 2
	v_pk_fma_f32 v[30:31], v[116:117], v[40:41], v[52:53]
	v_pk_fma_f32 v[38:39], v[112:113], v[38:39], v[50:51]
	v_lshlrev_b32_e32 v44, 2, v92
	global_load_dword v55, v44, s[42:43]
	global_load_dword v54, v44, s[42:43] offset:64
	global_load_dword v53, v44, s[42:43] offset:128
	global_load_dword v52, v44, s[42:43] offset:192
	global_load_dword v51, v44, s[42:43] offset:256
	global_load_dword v50, v44, s[42:43] offset:320
	global_load_dword v49, v44, s[42:43] offset:384
	global_load_dword v48, v44, s[42:43] offset:448
	v_pk_add_f32 v[44:45], v[24:25], 0 op_sel_hi:[1,0]
	v_pk_fma_f32 v[38:39], v[110:111], v[4:5], v[38:39]
	v_pk_add_f32 v[44:45], v[44:45], v[22:23]
	v_and_b32_e32 v5, 64, v198
	v_pk_add_f32 v[44:45], v[44:45], v[26:27]
	v_xor_b32_e32 v4, 1, v198
	v_pk_add_f32 v[44:45], v[44:45], v[28:29]
	v_add_u32_e32 v5, 64, v5
	v_pk_add_f32 v[44:45], v[44:45], v[32:33]
	v_cmp_lt_i32_e32 vcc, v4, v5
	v_pk_add_f32 v[44:45], v[44:45], v[34:35]
	v_pk_fma_f32 v[6:7], v[114:115], v[6:7], v[30:31]
	v_cndmask_b32_e32 v4, v198, v4, vcc
	v_mov_b32_e32 v30, v28
	v_mov_b32_e32 v31, v26
	v_mov_b32_e32 v26, v29
	v_pk_add_f32 v[28:29], v[44:45], v[36:37]
	v_lshlrev_b32_e32 v56, 2, v4
	v_pk_add_f32 v[28:29], v[28:29], v[38:39]
	v_xor_b32_e32 v4, 2, v198
	v_cmp_lt_i32_e32 vcc, v4, v5
	v_mov_b32_e32 v42, v34
	v_mov_b32_e32 v43, v32
	v_cndmask_b32_e32 v4, v198, v4, vcc
	v_lshlrev_b32_e32 v57, 2, v4
	s_waitcnt lgkmcnt(0)
	s_nop 1
	v_add_f32_dpp v28, v28, v28 quad_perm:[1,0,3,2] row_mask:0xf bank_mask:0xf
	v_add_f32_dpp v29, v29, v29 quad_perm:[1,0,3,2] row_mask:0xf bank_mask:0xf
	v_xor_b32_e32 v4, 4, v198
	v_cmp_lt_i32_e32 vcc, v4, v5
	v_mov_b32_e32 v32, v35
	v_mov_b32_e32 v36, v39
	v_cndmask_b32_e32 v4, v198, v4, vcc
	v_lshlrev_b32_e32 v58, 2, v4
	s_waitcnt lgkmcnt(0)
; __device__ __forceinline__ unsigned f2bf(float f) { return cvtpk(f, 0.f) & 0xffffu; }
; __device__ __forceinline__ void ret_out_phase(int l, LAS unsigned char* lds, int wave, int lane_) {
;     ...
;             s += __shfl_xor(s, 1); s += __shfl_xor(s, 2); s += __shfl_xor(s, 4); s += __shfl_xor(s, 8);
;             const float mean = s * (1.f / 128.f); float q = 0.f;
; #pragma unroll
;             for (int ob = 0; ob < 8; ++ob) { v[ob] -= mean; q += v[ob] * v[ob]; }
;             q += __shfl_xor(q, 1); q += __shfl_xor(q, 2); q += __shfl_xor(q, 4); q += __shfl_xor(q, 8);
;             const float rstd = rsqrtf(q * (1.f / 128.f) + 1e-6f);
;             bf16* yo = (bf16*)(ws + OFF_YB) + ((size_t)b * SEQ + j * RC + nl) * DM + h * 128;
;             const float* gn = p->in[I_RG] + (size_t)l * DM + h * 128;
; #pragma unroll
;             for (int ob = 0; ob < 8; ++ob) yo[ob * 16 + fr] = (bf16)f2bf(v[ob] * rstd * gn[ob * 16 + fr]);
	s_nop 1
	v_add_f32_dpp v28, v28, v28 quad_perm:[2,3,0,1] row_mask:0xf bank_mask:0xf
	v_add_f32_dpp v29, v29, v29 quad_perm:[2,3,0,1] row_mask:0xf bank_mask:0xf
	v_xor_b32_e32 v4, 8, v198
	v_cmp_lt_i32_e32 vcc, v4, v5
	v_mov_b32_e32 v60, v38
	s_mov_b32 s42, 0x358637bd
	v_cndmask_b32_e32 v4, v198, v4, vcc
	v_lshlrev_b32_e32 v59, 2, v4
	s_waitcnt lgkmcnt(0)
	s_nop 1
	v_add_f32_dpp v28, v28, v28 row_half_mirror row_mask:0xf bank_mask:0xf
	v_add_f32_dpp v29, v29, v29 row_half_mirror row_mask:0xf bank_mask:0xf
	v_lshl_add_u64 v[4:5], s[34:35], 0, v[100:101]
	v_lshlrev_b64 v[4:5], 11, v[4:5]
	v_lshl_add_u64 v[40:41], s[36:37], 0, v[4:5]
	v_lshlrev_b32_e32 v4, 1, v92
	s_waitcnt lgkmcnt(0)
	s_nop 1
	v_add_f32_dpp v28, v28, v28 row_mirror row_mask:0xf bank_mask:0xf
	v_add_f32_dpp v29, v29, v29 row_mirror row_mask:0xf bank_mask:0xf
	v_mov_b32_e32 v5, v3
	v_pk_mul_f32 v[62:63], v[28:29], s[86:87] op_sel_hi:[1,0]
	v_lshl_add_u64 v[40:41], v[40:41], 0, v[4:5]
	v_pk_add_f32 v[46:47], v[30:31], v[62:63] op_sel_hi:[1,0] neg_lo:[0,1] neg_hi:[0,1]
	v_pk_fma_f32 v[30:31], v[28:29], s[86:87], v[24:25] op_sel_hi:[1,0,1] neg_lo:[1,0,0] neg_hi:[1,0,0]
	v_pk_fma_f32 v[28:29], v[28:29], s[86:87], v[22:23] op_sel_hi:[1,0,1] neg_lo:[1,0,0] neg_hi:[1,0,0]
	v_pk_add_f32 v[26:27], v[26:27], v[62:63] op_sel:[0,1] neg_lo:[0,1] neg_hi:[0,1]
	v_pk_mul_f32 v[64:65], v[46:47], v[46:47]
	v_pk_mul_f32 v[22:23], v[28:29], v[28:29]
	v_pk_mul_f32 v[70:71], v[26:27], v[26:27]
	v_pk_add_f32 v[44:45], v[42:43], v[62:63] op_sel_hi:[1,0] neg_lo:[0,1] neg_hi:[0,1]
	v_pk_fma_f32 v[68:69], v[30:31], v[30:31], v[22:23]
	v_pk_add_f32 v[24:25], v[32:33], v[62:63] op_sel:[0,1] neg_lo:[0,1] neg_hi:[0,1]
	v_pk_add_f32 v[22:23], v[36:37], v[62:63] op_sel:[0,1] neg_lo:[0,1] neg_hi:[0,1]
	v_mov_b32_e32 v37, v64
	v_mov_b32_e32 v64, v71
	v_pk_mul_f32 v[66:67], v[44:45], v[44:45]
	v_pk_mul_f32 v[32:33], v[24:25], v[24:25]
	v_mov_b32_e32 v36, v70
	v_pk_add_f32 v[38:39], v[64:65], v[68:69] op_sel:[0,1] op_sel_hi:[1,0]
	v_pk_add_f32 v[42:43], v[60:61], v[62:63] op_sel_hi:[1,0] neg_lo:[0,1] neg_hi:[0,1]
	v_pk_add_f32 v[36:37], v[36:37], v[38:39]
	v_mov_b32_e32 v38, v33
	v_mov_b32_e32 v39, v67
	v_pk_mul_f32 v[60:61], v[42:43], v[42:43]
	v_pk_mul_f32 v[34:35], v[22:23], v[22:23]
	v_pk_add_f32 v[36:37], v[38:39], v[36:37]
	v_mov_b32_e32 v33, v66
	v_pk_add_f32 v[32:33], v[32:33], v[36:37]
	v_mov_b32_e32 v36, v35
	v_mov_b32_e32 v37, v61
	v_pk_add_f32 v[32:33], v[36:37], v[32:33]
	v_mov_b32_e32 v35, v60
	v_pk_add_f32 v[32:33], v[34:35], v[32:33]
	s_waitcnt lgkmcnt(0)
	s_nop 1
	v_add_f32_dpp v32, v32, v32 quad_perm:[1,0,3,2] row_mask:0xf bank_mask:0xf
	v_add_f32_dpp v33, v33, v33 quad_perm:[1,0,3,2] row_mask:0xf bank_mask:0xf
	s_waitcnt lgkmcnt(0)
	s_nop 1
	v_add_f32_dpp v32, v32, v32 quad_perm:[2,3,0,1] row_mask:0xf bank_mask:0xf
	v_add_f32_dpp v33, v33, v33 quad_perm:[2,3,0,1] row_mask:0xf bank_mask:0xf
	s_waitcnt lgkmcnt(0)
	s_nop 1
	v_add_f32_dpp v32, v32, v32 row_half_mirror row_mask:0xf bank_mask:0xf
	v_add_f32_dpp v33, v33, v33 row_half_mirror row_mask:0xf bank_mask:0xf
	s_waitcnt lgkmcnt(0)
	s_nop 1
	v_add_f32_dpp v34, v32, v32 row_mirror row_mask:0xf bank_mask:0xf
	v_add_f32_dpp v35, v33, v33 row_mirror row_mask:0xf bank_mask:0xf
	v_mov_b64_e32 v[32:33], s[42:43]
	v_pk_fma_f32 v[34:35], v[34:35], s[86:87], v[32:33] op_sel_hi:[1,0,0]
	s_nop 0
	v_mul_f32_e32 v36, 0x4b800000, v35
	v_cmp_gt_f32_e64 s[42:43], s19, v35
	v_cmp_gt_f32_e32 vcc, s19, v34
	s_nop 0
	v_cndmask_b32_e64 v35, v35, v36, s[42:43]
	v_rsq_f32_e32 v35, v35
	s_nop 0
	v_mul_f32_e32 v36, 0x45800000, v35
	v_cndmask_b32_e64 v35, v35, v36, s[42:43]
	v_mul_f32_e32 v28, v28, v35
	s_waitcnt vmcnt(6)
	v_mul_f32_e32 v28, v54, v28
	v_cvt_pk_bf16_f32 v28, v28, s0
	global_store_short v[40:41], v28, off offset:32
	v_mul_f32_e32 v28, v47, v35
	s_waitcnt vmcnt(6)
	v_mul_f32_e32 v28, v53, v28
	v_cvt_pk_bf16_f32 v28, v28, s0
	global_store_short v[40:41], v28, off offset:64
	v_mul_f32_e32 v28, v46, v35
	s_waitcnt vmcnt(6)
	v_mul_f32_e32 v28, v52, v28
	v_cvt_pk_bf16_f32 v28, v28, s0
	global_store_short v[40:41], v28, off offset:96
	v_mul_f32_e32 v28, v45, v35
	s_waitcnt vmcnt(6)
	v_mul_f32_e32 v28, v51, v28
	v_cvt_pk_bf16_f32 v28, v28, s0
	global_store_short v[40:41], v28, off offset:128
	v_mul_f32_e32 v28, v44, v35
	s_waitcnt vmcnt(6)
	v_mul_f32_e32 v28, v50, v28
	v_cvt_pk_bf16_f32 v28, v28, s0
	global_store_short v[40:41], v28, off offset:160
	v_mul_f32_e32 v28, v43, v35
	s_waitcnt vmcnt(6)
	v_mul_f32_e32 v28, v49, v28
	v_cvt_pk_bf16_f32 v28, v28, s0
	global_store_short v[40:41], v28, off offset:192
	v_mul_f32_e32 v28, v42, v35
	s_waitcnt vmcnt(6)
; __device__ __forceinline__ unsigned f2bf(float f) { return cvtpk(f, 0.f) & 0xffffu; }
; __device__ __forceinline__ void ret_out_phase(int l, LAS unsigned char* lds, int wave, int lane_) {
;     ...
;         for (int i = 0; i < 4; ++i) {
;             const int nl = 16 * wave + 4 * fq + i;
;             float v[8]; float s = 0.f;
; #pragma unroll
;             for (int ob = 0; ob < 8; ++ob) { v[ob] = y1[ob][i]; s += v[ob]; }
;             s += __shfl_xor(s, 1); s += __shfl_xor(s, 2); s += __shfl_xor(s, 4); s += __shfl_xor(s, 8);
;             const float mean = s * (1.f / 128.f); float q = 0.f;
; #pragma unroll
;             for (int ob = 0; ob < 8; ++ob) { v[ob] -= mean; q += v[ob] * v[ob]; }
;             q += __shfl_xor(q, 1); q += __shfl_xor(q, 2); q += __shfl_xor(q, 4); q += __shfl_xor(q, 8);
;             const float rstd = rsqrtf(q * (1.f / 128.f) + 1e-6f);
;             bf16* yo = (bf16*)(ws + OFF_YB) + ((size_t)b * SEQ + j * RC + nl) * DM + h * 128;
;             const float* gn = p->in[I_RG] + (size_t)l * DM + h * 128;
; #pragma unroll
;             for (int ob = 0; ob < 8; ++ob) yo[ob * 16 + fr] = (bf16)f2bf(v[ob] * rstd * gn[ob * 16 + fr]);
	v_mul_f32_e32 v28, v48, v28
	v_cvt_pk_bf16_f32 v28, v28, s0
	global_store_short v[40:41], v28, off offset:224
	v_mul_f32_e32 v28, 0x4b800000, v34
	v_cndmask_b32_e32 v28, v34, v28, vcc
	v_rsq_f32_e32 v28, v28
	v_mul_f32_e32 v30, v30, v35
	v_mul_f32_e32 v30, v55, v30
	v_cvt_pk_bf16_f32 v30, v30, s0
	global_store_short v[40:41], v30, off
	v_mul_f32_e32 v30, 0x45800000, v28
	v_cndmask_b32_e32 v28, v28, v30, vcc
	v_lshl_add_u64 v[34:35], s[34:35], 0, v[102:103]
	v_lshlrev_b64 v[34:35], 11, v[34:35]
	v_mul_f32_e32 v30, v31, v28
	v_mul_f32_e32 v29, v29, v28
	v_mul_f32_e32 v27, v27, v28
	v_mul_f32_e32 v26, v26, v28
	v_mul_f32_e32 v25, v25, v28
	v_mul_f32_e32 v24, v24, v28
	v_mul_f32_e32 v23, v23, v28
	v_mul_f32_e32 v22, v22, v28
	v_lshl_add_u64 v[34:35], s[36:37], 0, v[34:35]
	v_mul_f32_e32 v30, v55, v30
	v_mul_f32_e32 v29, v54, v29
	v_mul_f32_e32 v27, v53, v27
	v_mul_f32_e32 v26, v52, v26
	v_mul_f32_e32 v25, v51, v25
	v_mul_f32_e32 v24, v50, v24
	v_mul_f32_e32 v23, v49, v23
	v_mul_f32_e32 v22, v48, v22
	v_cvt_pk_bf16_f32 v36, v30, s0
	v_lshl_add_u64 v[30:31], v[34:35], 0, v[4:5]
	v_cvt_pk_bf16_f32 v29, v29, s0
	v_cvt_pk_bf16_f32 v27, v27, s0
	v_cvt_pk_bf16_f32 v26, v26, s0
	v_cvt_pk_bf16_f32 v25, v25, s0
	v_cvt_pk_bf16_f32 v24, v24, s0
	v_cvt_pk_bf16_f32 v23, v23, s0
	v_cvt_pk_bf16_f32 v22, v22, s0
	global_store_short v[30:31], v36, off
	global_store_short v[30:31], v29, off offset:32
	global_store_short v[30:31], v27, off offset:64
	global_store_short v[30:31], v26, off offset:96
	global_store_short v[30:31], v25, off offset:128
	global_store_short v[30:31], v24, off offset:160
	global_store_short v[30:31], v23, off offset:192
	global_store_short v[30:31], v22, off offset:224
	v_pk_add_f32 v[30:31], v[8:9], 0 op_sel_hi:[1,0]
	v_mov_b32_e32 v22, v14
	v_pk_add_f32 v[30:31], v[30:31], v[10:11]
	v_mov_b32_e32 v23, v12
	v_pk_add_f32 v[30:31], v[30:31], v[12:13]
	v_mov_b32_e32 v12, v15
	v_pk_add_f32 v[30:31], v[30:31], v[14:15]
	v_mov_b32_e32 v24, v18
	v_pk_add_f32 v[30:31], v[30:31], v[16:17]
	v_mov_b32_e32 v25, v16
	v_pk_add_f32 v[30:31], v[30:31], v[18:19]
	v_mov_b32_e32 v27, v20
	v_pk_add_f32 v[14:15], v[30:31], v[20:21]
	v_mov_b32_e32 v16, v19
	v_pk_add_f32 v[14:15], v[14:15], v[6:7]
	v_mov_b32_e32 v20, v7
	v_mov_b32_e32 v26, v6
	v_lshl_add_u64 v[28:29], s[34:35], 0, v[104:105]
	v_lshlrev_b64 v[28:29], 11, v[28:29]
	s_waitcnt lgkmcnt(0)
	s_nop 1
	v_add_f32_dpp v14, v14, v14 quad_perm:[1,0,3,2] row_mask:0xf bank_mask:0xf
	v_add_f32_dpp v15, v15, v15 quad_perm:[1,0,3,2] row_mask:0xf bank_mask:0xf
	v_lshl_add_u64 v[28:29], s[36:37], 0, v[28:29]
	v_lshl_add_u64 v[28:29], v[28:29], 0, v[4:5]
	s_waitcnt lgkmcnt(0)
	s_nop 1
	v_add_f32_dpp v14, v14, v14 quad_perm:[2,3,0,1] row_mask:0xf bank_mask:0xf
	v_add_f32_dpp v15, v15, v15 quad_perm:[2,3,0,1] row_mask:0xf bank_mask:0xf
	s_waitcnt lgkmcnt(0)
	s_nop 1
	v_add_f32_dpp v14, v14, v14 row_half_mirror row_mask:0xf bank_mask:0xf
	v_add_f32_dpp v15, v15, v15 row_half_mirror row_mask:0xf bank_mask:0xf
	s_waitcnt lgkmcnt(0)
	s_nop 1
	v_add_f32_dpp v14, v14, v14 row_mirror row_mask:0xf bank_mask:0xf
	v_add_f32_dpp v15, v15, v15 row_mirror row_mask:0xf bank_mask:0xf
	s_nop 0
	v_pk_mul_f32 v[30:31], v[14:15], s[86:87] op_sel_hi:[1,0]
	s_nop 0
	v_pk_add_f32 v[34:35], v[22:23], v[30:31] op_sel_hi:[1,0] neg_lo:[0,1] neg_hi:[0,1]
	v_pk_fma_f32 v[22:23], v[14:15], s[86:87], v[8:9] op_sel_hi:[1,0,1] neg_lo:[1,0,0] neg_hi:[1,0,0]
	v_pk_fma_f32 v[14:15], v[14:15], s[86:87], v[10:11] op_sel_hi:[1,0,1] neg_lo:[1,0,0] neg_hi:[1,0,0]
	v_pk_add_f32 v[10:11], v[12:13], v[30:31] op_sel:[0,1] neg_lo:[0,1] neg_hi:[0,1]
	v_pk_mul_f32 v[36:37], v[34:35], v[34:35]
	v_pk_mul_f32 v[8:9], v[14:15], v[14:15]
	v_pk_mul_f32 v[12:13], v[10:11], v[10:11]
	v_pk_add_f32 v[24:25], v[24:25], v[30:31] op_sel_hi:[1,0] neg_lo:[0,1] neg_hi:[0,1]
	v_pk_fma_f32 v[42:43], v[22:23], v[22:23], v[8:9]
	v_pk_add_f32 v[8:9], v[16:17], v[30:31] op_sel:[0,1] neg_lo:[0,1] neg_hi:[0,1]
	v_pk_add_f32 v[6:7], v[20:21], v[30:31] op_sel:[0,1] neg_lo:[0,1] neg_hi:[0,1]
	v_mov_b32_e32 v21, v36
	v_mov_b32_e32 v36, v13
	v_pk_mul_f32 v[38:39], v[24:25], v[24:25]
	v_pk_mul_f32 v[16:17], v[8:9], v[8:9]
	v_mov_b32_e32 v20, v12
	v_pk_add_f32 v[12:13], v[36:37], v[42:43] op_sel:[0,1] op_sel_hi:[1,0]
	v_pk_add_f32 v[26:27], v[26:27], v[30:31] op_sel_hi:[1,0] neg_lo:[0,1] neg_hi:[0,1]
	v_pk_add_f32 v[12:13], v[20:21], v[12:13]
	v_mov_b32_e32 v20, v17
	v_mov_b32_e32 v21, v39
	v_pk_mul_f32 v[40:41], v[26:27], v[26:27]
	v_pk_mul_f32 v[18:19], v[6:7], v[6:7]
	v_pk_add_f32 v[12:13], v[20:21], v[12:13]
	v_mov_b32_e32 v17, v38
	v_pk_add_f32 v[12:13], v[16:17], v[12:13]
	v_mov_b32_e32 v16, v19
	v_mov_b32_e32 v17, v41
	v_pk_add_f32 v[12:13], v[16:17], v[12:13]
	v_mov_b32_e32 v19, v40
	v_pk_add_f32 v[12:13], v[18:19], v[12:13]
	s_waitcnt lgkmcnt(0)
; __device__ __forceinline__ unsigned f2bf(float f) { return cvtpk(f, 0.f) & 0xffffu; }
; __device__ __forceinline__ void ret_out_phase(int l, LAS unsigned char* lds, int wave, int lane_) {
;     ...
;         for (int i = 0; i < 4; ++i) {
;             const int nl = 16 * wave + 4 * fq + i;
;             float v[8]; float s = 0.f;
; #pragma unroll
;             for (int ob = 0; ob < 8; ++ob) { v[ob] = y1[ob][i]; s += v[ob]; }
;             s += __shfl_xor(s, 1); s += __shfl_xor(s, 2); s += __shfl_xor(s, 4); s += __shfl_xor(s, 8);
;             const float mean = s * (1.f / 128.f); float q = 0.f;
; #pragma unroll
;             for (int ob = 0; ob < 8; ++ob) { v[ob] -= mean; q += v[ob] * v[ob]; }
;             q += __shfl_xor(q, 1); q += __shfl_xor(q, 2); q += __shfl_xor(q, 4); q += __shfl_xor(q, 8);
;             const float rstd = rsqrtf(q * (1.f / 128.f) + 1e-6f);
;             bf16* yo = (bf16*)(ws + OFF_YB) + ((size_t)b * SEQ + j * RC + nl) * DM + h * 128;
;             const float* gn = p->in[I_RG] + (size_t)l * DM + h * 128;
; #pragma unroll
;             for (int ob = 0; ob < 8; ++ob) yo[ob * 16 + fr] = (bf16)f2bf(v[ob] * rstd * gn[ob * 16 + fr]);
;         }
;         __syncthreads();
;     }
	s_nop 1
	v_add_f32_dpp v12, v12, v12 quad_perm:[1,0,3,2] row_mask:0xf bank_mask:0xf
	v_add_f32_dpp v13, v13, v13 quad_perm:[1,0,3,2] row_mask:0xf bank_mask:0xf
	s_waitcnt lgkmcnt(0)
	s_nop 1
	v_add_f32_dpp v12, v12, v12 quad_perm:[2,3,0,1] row_mask:0xf bank_mask:0xf
	v_add_f32_dpp v13, v13, v13 quad_perm:[2,3,0,1] row_mask:0xf bank_mask:0xf
	s_waitcnt lgkmcnt(0)
	s_nop 1
	v_add_f32_dpp v12, v12, v12 row_half_mirror row_mask:0xf bank_mask:0xf
	v_add_f32_dpp v13, v13, v13 row_half_mirror row_mask:0xf bank_mask:0xf
	s_waitcnt lgkmcnt(0)
	s_nop 1
	v_add_f32_dpp v12, v12, v12 row_mirror row_mask:0xf bank_mask:0xf
	v_add_f32_dpp v13, v13, v13 row_mirror row_mask:0xf bank_mask:0xf
	s_nop 0
	v_pk_fma_f32 v[12:13], v[12:13], s[86:87], v[32:33] op_sel_hi:[1,0,0]
	s_nop 0
	v_mul_f32_e32 v16, 0x4b800000, v13
	v_cmp_gt_f32_e64 s[42:43], s19, v13
	v_cmp_gt_f32_e32 vcc, s19, v12
	s_nop 0
	v_cndmask_b32_e64 v13, v13, v16, s[42:43]
	v_rsq_f32_e32 v13, v13
	s_nop 0
	v_mul_f32_e32 v16, 0x45800000, v13
	v_cndmask_b32_e64 v13, v13, v16, s[42:43]
	v_mul_f32_e32 v14, v14, v13
	v_mul_f32_e32 v14, v54, v14
	v_cvt_pk_bf16_f32 v14, v14, s0
	global_store_short v[28:29], v14, off offset:32
	v_mul_f32_e32 v14, v35, v13
	v_mul_f32_e32 v14, v53, v14
	v_cvt_pk_bf16_f32 v14, v14, s0
	global_store_short v[28:29], v14, off offset:64
	v_mul_f32_e32 v14, v34, v13
	v_mul_f32_e32 v14, v52, v14
	v_cvt_pk_bf16_f32 v14, v14, s0
	global_store_short v[28:29], v14, off offset:96
	v_mul_f32_e32 v14, v25, v13
	v_mul_f32_e32 v14, v51, v14
	v_cvt_pk_bf16_f32 v14, v14, s0
	global_store_short v[28:29], v14, off offset:128
	v_mul_f32_e32 v14, v24, v13
	v_mul_f32_e32 v14, v50, v14
	v_cvt_pk_bf16_f32 v14, v14, s0
	v_mul_f32_e32 v16, v22, v13
	global_store_short v[28:29], v14, off offset:160
	v_mul_f32_e32 v14, v27, v13
	v_mul_f32_e32 v13, v26, v13
	v_mul_f32_e32 v13, v48, v13
	v_cvt_pk_bf16_f32 v13, v13, s0
	global_store_short v[28:29], v13, off offset:224
	v_mul_f32_e32 v13, 0x4b800000, v12
	v_cndmask_b32_e32 v12, v12, v13, vcc
	v_rsq_f32_e32 v12, v12
	v_mul_f32_e32 v14, v49, v14
	v_cvt_pk_bf16_f32 v14, v14, s0
	global_store_short v[28:29], v14, off offset:192
	v_mul_f32_e32 v13, 0x45800000, v12
	v_cndmask_b32_e32 v14, v12, v13, vcc
	v_lshl_add_u64 v[12:13], s[34:35], 0, v[106:107]
	v_mul_f32_e32 v16, v55, v16
	v_lshlrev_b64 v[12:13], 11, v[12:13]
	v_cvt_pk_bf16_f32 v16, v16, s0
	v_lshl_add_u64 v[12:13], s[36:37], 0, v[12:13]
	global_store_short v[28:29], v16, off
	v_mul_f32_e32 v16, v23, v14
	v_lshl_add_u64 v[4:5], v[12:13], 0, v[4:5]
	v_mul_f32_e32 v12, v15, v14
	v_mul_f32_e32 v11, v11, v14
	v_mul_f32_e32 v10, v10, v14
	v_mul_f32_e32 v9, v9, v14
	v_mul_f32_e32 v8, v8, v14
	v_mul_f32_e32 v7, v7, v14
	v_mul_f32_e32 v6, v6, v14
	v_mul_f32_e32 v16, v55, v16
	v_mul_f32_e32 v12, v54, v12
	v_mul_f32_e32 v11, v53, v11
	v_mul_f32_e32 v10, v52, v10
	v_mul_f32_e32 v9, v51, v9
	v_mul_f32_e32 v8, v50, v8
	v_mul_f32_e32 v7, v49, v7
	v_mul_f32_e32 v6, v48, v6
	v_cvt_pk_bf16_f32 v16, v16, s0
	v_cvt_pk_bf16_f32 v12, v12, s0
	v_cvt_pk_bf16_f32 v11, v11, s0
	v_cvt_pk_bf16_f32 v10, v10, s0
	v_cvt_pk_bf16_f32 v9, v9, s0
	v_cvt_pk_bf16_f32 v8, v8, s0
	v_cvt_pk_bf16_f32 v7, v7, s0
	v_cvt_pk_bf16_f32 v6, v6, s0
	global_store_short v[4:5], v16, off
	global_store_short v[4:5], v12, off offset:32
	global_store_short v[4:5], v11, off offset:64
	global_store_short v[4:5], v10, off offset:96
	global_store_short v[4:5], v9, off offset:128
	global_store_short v[4:5], v8, off offset:160
	global_store_short v[4:5], v7, off offset:192
	global_store_short v[4:5], v6, off offset:224
	s_barrier
	s_cbranch_scc1 .LBB0_632
